# stack: E1 GEMM trims + saddr SP1 DMAs + attention QK 6-deep K prefetch + conditional prefetch drain + LDS-transposed wide-store epilogue
# baseline (speedup 1.0000x reference)
.LBB0_481:
	s_add_i32 s2, s44, 1
	ds_read_b128 v[228:231], v191 offset:49152
	ds_read_b128 v[232:235], v192 offset:49152
	ds_read_b128 v[236:239], v191 offset:57344
	ds_read_b128 v[240:243], v192 offset:57344
	ds_read_b128 v[244:247], v193 offset:49152
	ds_read_b128 v[248:251], v193 offset:57344
	s_cmp_ge_u32 s2, s34
	s_waitcnt lgkmcnt(5)
	v_mfma_f32_32x32x16_bf16 v[82:97], v[228:231], v[126:129], 0
	ds_read_b128 v[228:231], v194 offset:49152
	s_waitcnt lgkmcnt(5)
	v_mfma_f32_32x32x16_bf16 v[82:97], v[232:235], v[122:125], v[82:97]
	ds_read_b128 v[232:235], v194 offset:57344
	s_waitcnt lgkmcnt(5)
	v_mfma_f32_32x32x16_bf16 v[66:81], v[236:239], v[126:129], 0
	ds_read_b128 v[236:239], v195 offset:49152
	s_waitcnt lgkmcnt(5)
	v_mfma_f32_32x32x16_bf16 v[66:81], v[240:243], v[122:125], v[66:81]
	ds_read_b128 v[240:243], v195 offset:57344
	s_waitcnt lgkmcnt(5)
	v_mfma_f32_32x32x16_bf16 v[82:97], v[244:247], v[118:121], v[82:97]
	ds_read_b128 v[244:247], v196 offset:49152
	s_waitcnt lgkmcnt(5)
	v_mfma_f32_32x32x16_bf16 v[66:81], v[248:251], v[118:121], v[66:81]
	ds_read_b128 v[248:251], v196 offset:57344
	s_waitcnt lgkmcnt(5)
	v_mfma_f32_32x32x16_bf16 v[82:97], v[228:231], v[114:117], v[82:97]
	ds_read_b128 v[228:231], v197 offset:49152
	s_waitcnt lgkmcnt(5)
	v_mfma_f32_32x32x16_bf16 v[66:81], v[232:235], v[114:117], v[66:81]
	ds_read_b128 v[232:235], v197 offset:57344
	s_waitcnt lgkmcnt(5)
	v_mfma_f32_32x32x16_bf16 v[82:97], v[236:239], v[110:113], v[82:97]
	ds_read_b128 v[236:239], v198 offset:49152
	s_waitcnt lgkmcnt(5)
	v_mfma_f32_32x32x16_bf16 v[66:81], v[240:243], v[110:113], v[66:81]
	ds_read_b128 v[240:243], v198 offset:57344
	s_waitcnt lgkmcnt(5)
	v_mfma_f32_32x32x16_bf16 v[82:97], v[244:247], v[106:109], v[82:97]
	s_waitcnt lgkmcnt(4)
	v_mfma_f32_32x32x16_bf16 v[66:81], v[248:251], v[106:109], v[66:81]
	s_waitcnt lgkmcnt(3)
	v_mfma_f32_32x32x16_bf16 v[82:97], v[228:231], v[102:105], v[82:97]
	s_waitcnt lgkmcnt(2)
	v_mfma_f32_32x32x16_bf16 v[66:81], v[232:235], v[102:105], v[66:81]
	s_waitcnt lgkmcnt(1)
	v_mfma_f32_32x32x16_bf16 v[82:97], v[236:239], v[98:101], v[82:97]
	s_waitcnt lgkmcnt(0)
	v_mfma_f32_32x32x16_bf16 v[66:81], v[240:243], v[98:101], v[66:81]
	s_cbranch_scc1 .LBB0_484
	s_add_i32 s2, s29, s44
	s_add_i32 s3, s2, 1
	s_and_b32 s3, s3, 0x7ffffffe
	s_cmp_eq_u32 s3, 2
	s_cbranch_scc1 .LBB0_484
	s_cmp_eq_u32 s2, 0
	s_cselect_b64 vcc, -1, 0
	s_cmp_eq_u32 s2, 4
	v_cndmask_b32_e32 v162, -1, v200, vcc
	s_cselect_b64 vcc, -1, 0
	v_cndmask_b32_e32 v206, 64, v200, vcc
	v_sub_u32_e32 v162, v162, v199
	v_sub_u32_e32 v206, v206, v199
	v_cmp_lt_i32_e32 vcc, 0, v162
	v_cmp_gt_i32_e64 s[12:13], 0, v206
	s_or_b64 vcc, vcc, s[12:13]
	v_cndmask_b32_e32 v82, v82, v223, vcc
	v_cmp_lt_i32_e32 vcc, 32, v162
	v_cmp_gt_i32_e64 s[12:13], 32, v206
	s_or_b64 vcc, vcc, s[12:13]
	v_cndmask_b32_e32 v66, v66, v223, vcc
	v_cmp_lt_i32_e32 vcc, 1, v162
	v_cmp_gt_i32_e64 s[12:13], 1, v206
	s_or_b64 vcc, vcc, s[12:13]
	v_cndmask_b32_e32 v83, v83, v223, vcc
	v_cmp_lt_i32_e32 vcc, 33, v162
	v_cmp_gt_i32_e64 s[12:13], 33, v206
	s_or_b64 vcc, vcc, s[12:13]
	v_cndmask_b32_e32 v67, v67, v223, vcc
	v_cmp_lt_i32_e32 vcc, 2, v162
	v_cmp_gt_i32_e64 s[12:13], 2, v206
	s_or_b64 vcc, vcc, s[12:13]
	v_cndmask_b32_e32 v84, v84, v223, vcc
	v_cmp_lt_i32_e32 vcc, 34, v162
	v_cmp_gt_i32_e64 s[12:13], 34, v206
	s_or_b64 vcc, vcc, s[12:13]
	v_cndmask_b32_e32 v68, v68, v223, vcc
	v_cmp_lt_i32_e32 vcc, 3, v162
	v_cmp_gt_i32_e64 s[12:13], 3, v206
	s_or_b64 vcc, vcc, s[12:13]
	v_cndmask_b32_e32 v85, v85, v223, vcc
	v_cmp_lt_i32_e32 vcc, 35, v162
	v_cmp_gt_i32_e64 s[12:13], 35, v206
	s_or_b64 vcc, vcc, s[12:13]
	v_cndmask_b32_e32 v69, v69, v223, vcc
	v_cmp_lt_i32_e32 vcc, 8, v162
	v_cmp_gt_i32_e64 s[12:13], 8, v206
	s_or_b64 vcc, vcc, s[12:13]
	v_cndmask_b32_e32 v86, v86, v223, vcc
	v_cmp_lt_i32_e32 vcc, 40, v162
	v_cmp_gt_i32_e64 s[12:13], 40, v206
	s_or_b64 vcc, vcc, s[12:13]
	v_cndmask_b32_e32 v70, v70, v223, vcc
	v_cmp_lt_i32_e32 vcc, 9, v162
	v_cmp_gt_i32_e64 s[12:13], 9, v206
	s_or_b64 vcc, vcc, s[12:13]
	v_cndmask_b32_e32 v87, v87, v223, vcc
	v_cmp_lt_i32_e32 vcc, 41, v162
	v_cmp_gt_i32_e64 s[12:13], 41, v206
	s_or_b64 vcc, vcc, s[12:13]
	v_cndmask_b32_e32 v71, v71, v223, vcc
	v_cmp_lt_i32_e32 vcc, 10, v162
	v_cmp_gt_i32_e64 s[12:13], 10, v206
	s_or_b64 vcc, vcc, s[12:13]
	v_cndmask_b32_e32 v88, v88, v223, vcc
	v_cmp_lt_i32_e32 vcc, 42, v162
	v_cmp_gt_i32_e64 s[12:13], 42, v206
	s_or_b64 vcc, vcc, s[12:13]
	v_cndmask_b32_e32 v72, v72, v223, vcc
	v_cmp_lt_i32_e32 vcc, 11, v162
	v_cmp_gt_i32_e64 s[12:13], 11, v206
	s_or_b64 vcc, vcc, s[12:13]
	v_cndmask_b32_e32 v89, v89, v223, vcc
	v_cmp_lt_i32_e32 vcc, 43, v162
	v_cmp_gt_i32_e64 s[12:13], 43, v206
	s_or_b64 vcc, vcc, s[12:13]
	v_cndmask_b32_e32 v73, v73, v223, vcc
	v_cmp_lt_i32_e32 vcc, 16, v162
	v_cmp_gt_i32_e64 s[12:13], 16, v206
	s_or_b64 vcc, vcc, s[12:13]
	v_cndmask_b32_e32 v90, v90, v223, vcc
	v_cmp_lt_i32_e32 vcc, 48, v162
	v_cmp_gt_i32_e64 s[12:13], 48, v206
	s_or_b64 vcc, vcc, s[12:13]
	v_cndmask_b32_e32 v74, v74, v223, vcc
	v_cmp_lt_i32_e32 vcc, 17, v162
	v_cmp_gt_i32_e64 s[12:13], 17, v206
	s_or_b64 vcc, vcc, s[12:13]
	v_cndmask_b32_e32 v91, v91, v223, vcc
	v_cmp_lt_i32_e32 vcc, 49, v162
	v_cmp_gt_i32_e64 s[12:13], 49, v206
	s_or_b64 vcc, vcc, s[12:13]
	v_cndmask_b32_e32 v75, v75, v223, vcc
	v_cmp_lt_i32_e32 vcc, 18, v162
	v_cmp_gt_i32_e64 s[12:13], 18, v206
	s_or_b64 vcc, vcc, s[12:13]
	v_cndmask_b32_e32 v92, v92, v223, vcc
	v_cmp_lt_i32_e32 vcc, 50, v162
	v_cmp_gt_i32_e64 s[12:13], 50, v206
	s_or_b64 vcc, vcc, s[12:13]
	v_cndmask_b32_e32 v76, v76, v223, vcc
	v_cmp_lt_i32_e32 vcc, 19, v162
	v_cmp_gt_i32_e64 s[12:13], 19, v206
	s_or_b64 vcc, vcc, s[12:13]
	v_cndmask_b32_e32 v93, v93, v223, vcc
	v_cmp_lt_i32_e32 vcc, 51, v162
	v_cmp_gt_i32_e64 s[12:13], 51, v206
	s_or_b64 vcc, vcc, s[12:13]
	v_cndmask_b32_e32 v77, v77, v223, vcc
	v_cmp_lt_i32_e32 vcc, 24, v162
	v_cmp_gt_i32_e64 s[12:13], 24, v206
	s_or_b64 vcc, vcc, s[12:13]
	v_cndmask_b32_e32 v94, v94, v223, vcc
	v_cmp_lt_i32_e32 vcc, 56, v162
	v_cmp_gt_i32_e64 s[12:13], 56, v206
	s_or_b64 vcc, vcc, s[12:13]
	v_cndmask_b32_e32 v78, v78, v223, vcc
	v_cmp_lt_i32_e32 vcc, 25, v162
	v_cmp_gt_i32_e64 s[12:13], 25, v206
	s_or_b64 vcc, vcc, s[12:13]
	v_cndmask_b32_e32 v95, v95, v223, vcc
	v_cmp_lt_i32_e32 vcc, 57, v162
	v_cmp_gt_i32_e64 s[12:13], 57, v206
	s_or_b64 vcc, vcc, s[12:13]
	v_cndmask_b32_e32 v79, v79, v223, vcc
	v_cmp_lt_i32_e32 vcc, 26, v162
	v_cmp_gt_i32_e64 s[12:13], 26, v206
	s_or_b64 vcc, vcc, s[12:13]
	v_cndmask_b32_e32 v96, v96, v223, vcc
	v_cmp_lt_i32_e32 vcc, 58, v162
	v_cmp_gt_i32_e64 s[12:13], 58, v206
	s_or_b64 vcc, vcc, s[12:13]
	v_cndmask_b32_e32 v80, v80, v223, vcc
	v_cmp_lt_i32_e32 vcc, 27, v162
	v_cmp_gt_i32_e64 s[12:13], 27, v206
	s_or_b64 vcc, vcc, s[12:13]
	v_cndmask_b32_e32 v97, v97, v223, vcc
	v_cmp_lt_i32_e32 vcc, 59, v162
	v_cmp_gt_i32_e64 s[12:13], 59, v206
	s_or_b64 vcc, vcc, s[12:13]
	v_cndmask_b32_e32 v81, v81, v223, vcc

.LBB0_488:
	v_cndmask_b32_e64 v226, v162, v166, s[12:13]
	v_mul_f32_e32 v227, 0xbe0293ee, v226
	v_fmamk_f32 v82, v82, 0x3e0293ee, v227
	v_fmamk_f32 v83, v83, 0x3e0293ee, v227
	v_fmamk_f32 v84, v84, 0x3e0293ee, v227
	v_fmamk_f32 v85, v85, 0x3e0293ee, v227
	v_fmamk_f32 v86, v86, 0x3e0293ee, v227
	v_fmamk_f32 v87, v87, 0x3e0293ee, v227
	v_fmamk_f32 v88, v88, 0x3e0293ee, v227
	v_fmamk_f32 v89, v89, 0x3e0293ee, v227
	v_fmamk_f32 v90, v90, 0x3e0293ee, v227
	v_fmamk_f32 v91, v91, 0x3e0293ee, v227
	v_fmamk_f32 v92, v92, 0x3e0293ee, v227
	v_fmamk_f32 v93, v93, 0x3e0293ee, v227
	v_fmamk_f32 v94, v94, 0x3e0293ee, v227
	v_fmamk_f32 v95, v95, 0x3e0293ee, v227
	v_fmamk_f32 v96, v96, 0x3e0293ee, v227
	v_fmamk_f32 v97, v97, 0x3e0293ee, v227
	v_exp_f32_e32 v162, v82
	v_exp_f32_e32 v177, v83
	v_exp_f32_e32 v163, v84
	v_exp_f32_e32 v176, v85
	v_exp_f32_e32 v164, v86
	v_exp_f32_e32 v175, v87
	v_exp_f32_e32 v165, v88
	v_exp_f32_e32 v174, v89
	v_exp_f32_e32 v166, v90
	v_exp_f32_e32 v173, v91
	v_exp_f32_e32 v167, v92
	v_exp_f32_e32 v172, v93
	v_exp_f32_e32 v168, v94
	v_exp_f32_e32 v171, v95
	v_exp_f32_e32 v169, v96
	v_exp_f32_e32 v170, v97
	v_fmamk_f32 v229, v66, 0x3e0293ee, v227
	v_fmamk_f32 v230, v67, 0x3e0293ee, v227
	v_fmamk_f32 v231, v68, 0x3e0293ee, v227
	v_fmamk_f32 v232, v69, 0x3e0293ee, v227
	v_fmamk_f32 v233, v70, 0x3e0293ee, v227
	v_fmamk_f32 v234, v71, 0x3e0293ee, v227
	v_fmamk_f32 v235, v72, 0x3e0293ee, v227
	v_fmamk_f32 v236, v73, 0x3e0293ee, v227
	v_fmamk_f32 v237, v74, 0x3e0293ee, v227
	v_fmamk_f32 v238, v75, 0x3e0293ee, v227
	v_fmamk_f32 v239, v76, 0x3e0293ee, v227
	v_fmamk_f32 v240, v77, 0x3e0293ee, v227
	v_fmamk_f32 v241, v78, 0x3e0293ee, v227
	v_fmamk_f32 v242, v79, 0x3e0293ee, v227
	v_fmamk_f32 v243, v80, 0x3e0293ee, v227
	v_fmac_f32_e32 v227, 0x3e0293ee, v81
	s_add_i32 s45, s44, 2
	s_waitcnt lgkmcnt(0)
	s_barrier
	ds_read_b128 v[244:247], v191 offset:32768
	ds_read_b128 v[248:251], v192 offset:32768
	ds_read_b128 v[130:133], v191 offset:40960
	ds_read_b128 v[134:137], v192 offset:40960
	ds_read_b128 v[138:141], v193 offset:32768
	ds_read_b128 v[142:145], v193 offset:40960
	s_cmp_ge_u32 s45, s34
	s_waitcnt lgkmcnt(5)
	v_mfma_f32_32x32x16_bf16 v[82:97], v[244:247], v[126:129], 0
	ds_read_b128 v[244:247], v194 offset:32768
	s_waitcnt lgkmcnt(5)
	v_mfma_f32_32x32x16_bf16 v[82:97], v[248:251], v[122:125], v[82:97]
	ds_read_b128 v[248:251], v194 offset:40960
	s_waitcnt lgkmcnt(5)
	v_mfma_f32_32x32x16_bf16 v[66:81], v[130:133], v[126:129], 0
	ds_read_b128 v[130:133], v195 offset:32768
	s_waitcnt lgkmcnt(5)
	v_mfma_f32_32x32x16_bf16 v[66:81], v[134:137], v[122:125], v[66:81]
	ds_read_b128 v[134:137], v195 offset:40960
	s_waitcnt lgkmcnt(5)
	v_mfma_f32_32x32x16_bf16 v[82:97], v[138:141], v[118:121], v[82:97]
	ds_read_b128 v[138:141], v196 offset:32768
	s_waitcnt lgkmcnt(5)
	v_mfma_f32_32x32x16_bf16 v[66:81], v[142:145], v[118:121], v[66:81]
	ds_read_b128 v[142:145], v196 offset:40960
	s_waitcnt lgkmcnt(5)
	v_mfma_f32_32x32x16_bf16 v[82:97], v[244:247], v[114:117], v[82:97]
	ds_read_b128 v[244:247], v197 offset:32768
	s_waitcnt lgkmcnt(5)
	v_mfma_f32_32x32x16_bf16 v[66:81], v[248:251], v[114:117], v[66:81]
	ds_read_b128 v[248:251], v197 offset:40960
	s_waitcnt lgkmcnt(5)
	v_mfma_f32_32x32x16_bf16 v[82:97], v[130:133], v[110:113], v[82:97]
	ds_read_b128 v[130:133], v198 offset:32768
	s_waitcnt lgkmcnt(5)
	v_mfma_f32_32x32x16_bf16 v[66:81], v[134:137], v[110:113], v[66:81]
	ds_read_b128 v[134:137], v198 offset:40960
	s_waitcnt lgkmcnt(5)
	v_mfma_f32_32x32x16_bf16 v[82:97], v[138:141], v[106:109], v[82:97]
	s_waitcnt lgkmcnt(4)
	v_mfma_f32_32x32x16_bf16 v[66:81], v[142:145], v[106:109], v[66:81]
	s_waitcnt lgkmcnt(3)
	v_mfma_f32_32x32x16_bf16 v[82:97], v[244:247], v[102:105], v[82:97]
	s_waitcnt lgkmcnt(2)
	v_mfma_f32_32x32x16_bf16 v[66:81], v[248:251], v[102:105], v[66:81]
	s_waitcnt lgkmcnt(1)
	v_mfma_f32_32x32x16_bf16 v[82:97], v[130:133], v[98:101], v[82:97]
	s_waitcnt lgkmcnt(0)
	v_mfma_f32_32x32x16_bf16 v[66:81], v[134:137], v[98:101], v[66:81]
	s_cbranch_scc1 .LBB0_491
	s_add_i32 s2, s29, s44
	s_add_i32 s3, s2, 2
	s_and_b32 s3, s3, 0x7ffffffe
	s_cmp_eq_u32 s3, 2
	s_cbranch_scc1 .LBB0_491
	s_cmp_eq_u32 s2, 2
	s_cselect_b64 vcc, -1, 0
	v_cndmask_b32_e32 v244, 64, v183, vcc
	v_sub_u32_e32 v244, v244, v199
	v_cmp_lt_i32_e32 vcc, -1, v244
	s_nop 1
	v_cndmask_b32_e32 v82, v223, v82, vcc
	v_cmp_lt_i32_e32 vcc, 31, v244
	s_nop 1
	v_cndmask_b32_e32 v66, v223, v66, vcc
	v_cmp_lt_i32_e32 vcc, 0, v244
	s_nop 1
	v_cndmask_b32_e32 v83, v223, v83, vcc
	v_cmp_lt_i32_e32 vcc, 32, v244
	s_nop 1
	v_cndmask_b32_e32 v67, v223, v67, vcc
	v_cmp_lt_i32_e32 vcc, 1, v244
	s_nop 1
	v_cndmask_b32_e32 v84, v223, v84, vcc
	v_cmp_lt_i32_e32 vcc, 33, v244
	s_nop 1
	v_cndmask_b32_e32 v68, v223, v68, vcc
	v_cmp_lt_i32_e32 vcc, 2, v244
	s_nop 1
	v_cndmask_b32_e32 v85, v223, v85, vcc
	v_cmp_lt_i32_e32 vcc, 34, v244
	s_nop 1
	v_cndmask_b32_e32 v69, v223, v69, vcc
	v_cmp_lt_i32_e32 vcc, 7, v244
	s_nop 1
	v_cndmask_b32_e32 v86, v223, v86, vcc
	v_cmp_lt_i32_e32 vcc, 39, v244
	s_nop 1
	v_cndmask_b32_e32 v70, v223, v70, vcc
	v_cmp_lt_i32_e32 vcc, 8, v244
	s_nop 1
	v_cndmask_b32_e32 v87, v223, v87, vcc
	v_cmp_lt_i32_e32 vcc, 40, v244
	s_nop 1
	v_cndmask_b32_e32 v71, v223, v71, vcc
	v_cmp_lt_i32_e32 vcc, 9, v244
	s_nop 1
	v_cndmask_b32_e32 v88, v223, v88, vcc
	v_cmp_lt_i32_e32 vcc, 41, v244
	s_nop 1
	v_cndmask_b32_e32 v72, v223, v72, vcc
	v_cmp_lt_i32_e32 vcc, 10, v244
	s_nop 1
	v_cndmask_b32_e32 v89, v223, v89, vcc
	v_cmp_lt_i32_e32 vcc, 42, v244
	s_nop 1
	v_cndmask_b32_e32 v73, v223, v73, vcc
	v_cmp_lt_i32_e32 vcc, 15, v244
	s_nop 1
	v_cndmask_b32_e32 v90, v223, v90, vcc
	v_cmp_lt_i32_e32 vcc, 47, v244
	s_nop 1
	v_cndmask_b32_e32 v74, v223, v74, vcc
	v_cmp_lt_i32_e32 vcc, 16, v244
	s_nop 1
	v_cndmask_b32_e32 v91, v223, v91, vcc
	v_cmp_lt_i32_e32 vcc, 48, v244
	s_nop 1
	v_cndmask_b32_e32 v75, v223, v75, vcc
	v_cmp_lt_i32_e32 vcc, 17, v244
	s_nop 1
	v_cndmask_b32_e32 v92, v223, v92, vcc
	v_cmp_lt_i32_e32 vcc, 49, v244
	s_nop 1
	v_cndmask_b32_e32 v76, v223, v76, vcc
	v_cmp_lt_i32_e32 vcc, 18, v244
	s_nop 1
	v_cndmask_b32_e32 v93, v223, v93, vcc
	v_cmp_lt_i32_e32 vcc, 50, v244
	s_nop 1
	v_cndmask_b32_e32 v77, v223, v77, vcc
	v_cmp_lt_i32_e32 vcc, 23, v244
	s_nop 1
	v_cndmask_b32_e32 v94, v223, v94, vcc
	v_cmp_lt_i32_e32 vcc, 55, v244
	s_nop 1
	v_cndmask_b32_e32 v78, v223, v78, vcc
	v_cmp_lt_i32_e32 vcc, 24, v244
	s_nop 1
	v_cndmask_b32_e32 v95, v223, v95, vcc
	v_cmp_lt_i32_e32 vcc, 56, v244
	s_nop 1
	v_cndmask_b32_e32 v79, v223, v79, vcc
	v_cmp_lt_i32_e32 vcc, 25, v244
	s_nop 1
	v_cndmask_b32_e32 v96, v223, v96, vcc
	v_cmp_lt_i32_e32 vcc, 57, v244
	s_nop 1
	v_cndmask_b32_e32 v80, v223, v80, vcc
	v_cmp_lt_i32_e32 vcc, 26, v244
	s_nop 1
	v_cndmask_b32_e32 v97, v223, v97, vcc
	v_cmp_lt_i32_e32 vcc, 58, v244
	s_nop 1
	v_cndmask_b32_e32 v81, v223, v81, vcc

.LBB0_493:
	ds_read_b64_tr_b16 v[232:233], v189 offset:0
	ds_read_b64_tr_b16 v[234:235], v189 offset:0x800
	ds_read_b64_tr_b16 v[236:237], v189 offset:0x1000
	ds_read_b64_tr_b16 v[238:239], v189 offset:0x1800
	ds_read_b64_tr_b16 v[240:241], v189 offset:0x2000
	ds_read_b64_tr_b16 v[242:243], v189 offset:0x2800
	ds_read_b64_tr_b16 v[244:245], v189 offset:0x3000
	ds_read_b64_tr_b16 v[246:247], v189 offset:0x3800
	s_waitcnt lgkmcnt(0)
	s_nop 0
	v_mfma_f32_32x32x16_bf16 v[2:17], v[162:165], v[232:235], v[2:17]
	ds_read_b64_tr_b16 v[232:233], v189 offset:0x200
	ds_read_b64_tr_b16 v[234:235], v189 offset:0xa00
	v_mfma_f32_32x32x16_bf16 v[2:17], v[166:169], v[236:239], v[2:17]
	ds_read_b64_tr_b16 v[236:237], v189 offset:0x1200
	ds_read_b64_tr_b16 v[238:239], v189 offset:0x1a00
	v_mfma_f32_32x32x16_bf16 v[2:17], v[170:173], v[240:243], v[2:17]
	ds_read_b64_tr_b16 v[240:241], v189 offset:0x2200
	ds_read_b64_tr_b16 v[242:243], v189 offset:0x2a00
	v_mfma_f32_32x32x16_bf16 v[2:17], v[174:177], v[244:247], v[2:17]
	ds_read_b64_tr_b16 v[244:245], v189 offset:0x3200
	ds_read_b64_tr_b16 v[246:247], v189 offset:0x3a00
	s_waitcnt lgkmcnt(0)
	v_mfma_f32_32x32x16_bf16 v[50:65], v[162:165], v[232:235], v[50:65]
	ds_read_b64_tr_b16 v[232:233], v189 offset:0x400
	ds_read_b64_tr_b16 v[234:235], v189 offset:0xc00
	v_mfma_f32_32x32x16_bf16 v[50:65], v[166:169], v[236:239], v[50:65]
	ds_read_b64_tr_b16 v[236:237], v189 offset:0x1400
	ds_read_b64_tr_b16 v[238:239], v189 offset:0x1c00
	v_mfma_f32_32x32x16_bf16 v[50:65], v[170:173], v[240:243], v[50:65]
	ds_read_b64_tr_b16 v[240:241], v189 offset:0x2400
	ds_read_b64_tr_b16 v[242:243], v189 offset:0x2c00
	v_mfma_f32_32x32x16_bf16 v[50:65], v[174:177], v[244:247], v[50:65]
	ds_read_b64_tr_b16 v[244:245], v189 offset:0x3400
	ds_read_b64_tr_b16 v[246:247], v189 offset:0x3c00
	s_waitcnt lgkmcnt(0)
	v_mfma_f32_32x32x16_bf16 v[34:49], v[162:165], v[232:235], v[34:49]
	ds_read_b64_tr_b16 v[232:233], v189 offset:0x600
	ds_read_b64_tr_b16 v[234:235], v189 offset:0xe00
	v_mfma_f32_32x32x16_bf16 v[34:49], v[166:169], v[236:239], v[34:49]
	ds_read_b64_tr_b16 v[236:237], v189 offset:0x1600
	ds_read_b64_tr_b16 v[238:239], v189 offset:0x1e00
	v_mfma_f32_32x32x16_bf16 v[34:49], v[170:173], v[240:243], v[34:49]
	ds_read_b64_tr_b16 v[240:241], v189 offset:0x2600
	ds_read_b64_tr_b16 v[242:243], v189 offset:0x2e00
	v_mfma_f32_32x32x16_bf16 v[34:49], v[174:177], v[244:247], v[34:49]
	ds_read_b64_tr_b16 v[244:245], v189 offset:0x3600
	ds_read_b64_tr_b16 v[246:247], v189 offset:0x3e00
	s_waitcnt lgkmcnt(0)
	v_mfma_f32_32x32x16_bf16 v[18:33], v[162:165], v[232:235], v[18:33]
	v_max_f32_e32 v162, v83, v83
	v_max_f32_e32 v163, v82, v82
	v_max_f32_e32 v162, v163, v162
	v_max3_f32 v162, v162, v84, v85
	v_max3_f32 v162, v162, v86, v87
	v_max3_f32 v162, v162, v88, v89
	v_max3_f32 v162, v162, v90, v91
	v_max3_f32 v162, v162, v92, v93
	v_max3_f32 v162, v162, v94, v95
	v_mfma_f32_32x32x16_bf16 v[18:33], v[166:169], v[236:239], v[18:33]
	v_max3_f32 v162, v162, v96, v97
	v_max3_f32 v162, v162, v66, v67
	v_max3_f32 v162, v162, v68, v69
	v_max3_f32 v162, v162, v70, v71
	v_max3_f32 v162, v162, v72, v73
	v_max3_f32 v162, v162, v74, v75
	v_max3_f32 v162, v162, v76, v77
	v_max3_f32 v162, v162, v78, v79
	v_mfma_f32_32x32x16_bf16 v[18:33], v[170:173], v[240:243], v[18:33]
	v_max3_f32 v162, v162, v80, v81
	v_mov_b32_e32 v163, v162
	s_nop 1
	v_permlane32_swap_b32_e32 v162, v163
	v_max_f32_e32 v163, v163, v163
	v_max_f32_e32 v162, v162, v162
	v_max_f32_e32 v162, v162, v163
	v_sub_f32_e32 v163, v162, v226
	v_cmp_ge_f32_e32 vcc, s49, v163
	v_max_f32_e32 v163, v226, v226
	v_max_f32_e32 v163, v163, v162
	v_mfma_f32_32x32x16_bf16 v[18:33], v[174:177], v[244:247], v[18:33]
	v_sub_f32_e32 v162, v226, v163
	v_mul_f32_e32 v162, 0x3e0293ee, v162
	v_exp_f32_e32 v162, v162
	s_cmp_eq_u64 vcc, exec
	s_cselect_b64 s[12:13], -1, 0
	s_barrier
	s_waitcnt vmcnt(4)
	v_cndmask_b32_e64 v162, v162, 1.0, s[12:13]
	v_cmp_gt_f32_e32 vcc, 1.0, v162
	s_add_i32 s2, s44, 4
	s_cmp_ge_u32 s2, s7
	s_cbranch_scc0 .Lattn_keep_prefetch
	s_waitcnt vmcnt(0)
.Lattn_keep_prefetch:
	ds_write_b128 v184, v[146:149] offset:16384
	ds_write_b128 v185, v[158:161] offset:16384
	ds_write_b128 v187, v[150:153] offset:49152
	ds_write_b128 v188, v[154:157] offset:49152
	s_cbranch_vccz .LBB0_497
	s_and_saveexec_b64 s[2:3], s[10:11]
	ds_write_b32 v186, v162 offset:128
	s_or_b64 exec, exec, s[2:3]
	s_waitcnt lgkmcnt(0)
	v_add_u32_e32 v158, v179, v178
	ds_read_b128 v[146:149], v158 offset:224
	ds_read_b128 v[150:153], v158 offset:192
	ds_read_b128 v[154:157], v158 offset:160
	ds_read_b128 v[158:161], v158 offset:128
	s_waitcnt lgkmcnt(3)
	v_pk_mul_f32 v[14:15], v[14:15], v[146:147]
	s_waitcnt lgkmcnt(2)
	v_pk_mul_f32 v[10:11], v[10:11], v[150:151]
	s_waitcnt lgkmcnt(1)
	v_pk_mul_f32 v[6:7], v[6:7], v[154:155]
	v_pk_mul_f32 v[16:17], v[16:17], v[148:149]
	v_pk_mul_f32 v[12:13], v[12:13], v[152:153]
	v_pk_mul_f32 v[8:9], v[8:9], v[156:157]
	s_waitcnt lgkmcnt(0)
	v_pk_mul_f32 v[4:5], v[4:5], v[160:161]
	v_pk_mul_f32 v[2:3], v[2:3], v[158:159]
	v_pk_mul_f32 v[62:63], v[62:63], v[146:147]
	v_pk_mul_f32 v[58:59], v[58:59], v[150:151]
	v_pk_mul_f32 v[54:55], v[54:55], v[154:155]
	v_pk_mul_f32 v[64:65], v[64:65], v[148:149]
	v_pk_mul_f32 v[60:61], v[60:61], v[152:153]
	v_pk_mul_f32 v[56:57], v[56:57], v[156:157]
	v_pk_mul_f32 v[52:53], v[52:53], v[160:161]
	v_pk_mul_f32 v[50:51], v[50:51], v[158:159]
	v_pk_mul_f32 v[46:47], v[46:47], v[146:147]
	v_pk_mul_f32 v[42:43], v[42:43], v[150:151]
	v_pk_mul_f32 v[38:39], v[38:39], v[154:155]
	v_pk_mul_f32 v[48:49], v[48:49], v[148:149]
	v_pk_mul_f32 v[44:45], v[44:45], v[152:153]
	v_pk_mul_f32 v[40:41], v[40:41], v[156:157]
	v_pk_mul_f32 v[36:37], v[36:37], v[160:161]
	v_pk_mul_f32 v[34:35], v[34:35], v[158:159]
	v_pk_mul_f32 v[30:31], v[30:31], v[146:147]
	v_pk_mul_f32 v[26:27], v[26:27], v[150:151]
	v_pk_mul_f32 v[22:23], v[22:23], v[154:155]
	v_pk_mul_f32 v[32:33], v[32:33], v[148:149]
	v_pk_mul_f32 v[28:29], v[28:29], v[152:153]
	v_pk_mul_f32 v[24:25], v[24:25], v[156:157]
	v_pk_mul_f32 v[20:21], v[20:21], v[160:161]
	v_pk_mul_f32 v[18:19], v[18:19], v[158:159]
